# diff-attn main tile loop: PV phase k-step-major with exp/pack interleaved under MFMAs; leading-half LDS-DMA pieces spread through PV phase (SGPR-base form); QK phase: bias block as MFMA C operand, no
# speedup vs baseline: 1.1160x; 1.1160x over previous
.LBB0_258:
	s_mov_b32 s98, 0
	s_mul_i32 s27, s64, s96
	v_readlane_b32 s12, v255, 10
	s_add_i32 s27, s27, s12
	s_bfe_u32 s14, s27, 0x20004
	s_lshl_b32 s12, s14, 11
	v_add_u32_e32 v1, v0, v157
	s_add_i32 s22, s12, 0
	ds_read_b128 v[52:55], v1
	ds_read_b128 v[8:11], v1 offset:4096
	v_add_u32_e32 v1, v0, v193
	s_add_i32 s22, s22, 0x20000
	ds_read_b128 v[56:59], v1
	ds_read_b128 v[12:15], v1 offset:4096
	v_add_u32_e32 v1, v0, v208
	v_add_u32_e32 v4, v0, v209
	v_mov_b32_e32 v16, s22
	ds_read_b128 v[60:63], v1
	ds_read_b128 v[48:51], v1 offset:4096
	ds_read_b128 v[0:3], v4
	ds_read_b128 v[4:7], v4 offset:4096
	ds_read_b32 v145, v16
	ds_read_b32 v152, v16 offset:2040
	s_andn2_b64 vcc, exec, s[18:19]
	s_cbranch_vccnz .LBB0_260
	s_barrier

.LBB0_272:
	s_andn2_b64 vcc, exec, s[54:55]
	s_cbranch_vccnz .LBB0_274
	s_add_i32 s54, s36, 0x7a
	s_cmpk_lt_i32 s54, 0xff67
	s_cselect_b32 s99, 1, 2
	s_cmp_eq_u32 s99, s98
	s_cbranch_scc1 .Lattn_cb_ok
	s_cmp_eq_u32 s99, 1
	s_cselect_b64 vcc, -1, 0
	s_mov_b32 s98, s99
	v_cndmask_b32_e32 v168, v152, v145, vcc
	v_sub_f32_e32 v168, v168, v207
	v_mov_b32_e32 v169, v168
	v_mov_b32_e32 v170, v168
	v_mov_b32_e32 v171, v168
	v_mov_b32_e32 v172, v168
	v_mov_b32_e32 v173, v168
	v_mov_b32_e32 v174, v168
	v_mov_b32_e32 v175, v168
	v_mov_b32_e32 v176, v168
	v_mov_b32_e32 v177, v168
	v_mov_b32_e32 v178, v168
	v_mov_b32_e32 v179, v168
	v_mov_b32_e32 v180, v168
	v_mov_b32_e32 v181, v168
	v_mov_b32_e32 v182, v168
	v_mov_b32_e32 v183, v168
	s_nop 1
.Lattn_cb_ok:
	v_mfma_f32_32x32x16_bf16 v[64:79], v[132:135], v[108:111], v[168:183]
	s_add_i32 s54, s65, 0xffff8000
	s_and_b32 s54, s54, 0x18000
	v_mfma_f32_32x32x16_bf16 v[80:95], v[116:119], v[108:111], v[168:183]
	s_branch .Lattn_qk_rest

.Lattn_qk_rest:
	v_add_u32_e32 v116, s54, v214
	v_add_u32_e32 v216, v116, v157
	v_add_u32_e32 v218, v116, v208
	v_add_u32_e32 v217, v116, v193
	v_add_u32_e32 v219, v116, v209
	v_mfma_f32_32x32x16_bf16 v[64:79], v[136:139], v[104:107], v[64:79]
	v_mfma_f32_32x32x16_bf16 v[80:95], v[120:123], v[104:107], v[80:95]
	v_mfma_f32_32x32x16_bf16 v[64:79], v[140:143], v[100:103], v[64:79]
	v_mfma_f32_32x32x16_bf16 v[80:95], v[124:127], v[100:103], v[80:95]
	v_mfma_f32_32x32x16_bf16 v[80:95], v[112:115], v[96:99], v[80:95]
	ds_read_b128 v[120:123], v216 offset:16384
	ds_read_b128 v[112:115], v216 offset:20480
	ds_read_b128 v[124:127], v216 offset:24576
	ds_read_b128 v[116:119], v216 offset:28672
	v_mfma_f32_32x32x16_bf16 v[64:79], v[128:131], v[96:99], v[64:79]
	s_nop 11
	v_max_f32_e32 v128, v65, v65
	v_max_f32_e32 v129, v64, v64
	v_max_f32_e32 v128, v129, v128
	v_max3_f32 v129, v66, v67, v81
	v_max3_f32 v128, v128, v80, v82
	v_max3_f32 v128, v128, v83, v68
	v_max3_f32 v129, v129, v70, v71
	v_max3_f32 v128, v128, v69, v84
	v_max3_f32 v129, v129, v86, v87
	v_max3_f32 v128, v128, v85, v72
	v_max3_f32 v129, v129, v74, v75
	v_max3_f32 v128, v128, v73, v88
	v_max3_f32 v129, v129, v90, v91
	v_max3_f32 v128, v128, v89, v76
	v_max3_f32 v129, v129, v78, v79
	v_max3_f32 v128, v128, v77, v92
	v_max3_f32 v129, v129, v94, v95
	v_max3_f32 v128, v128, v93, v129
	v_cmp_lt_f32_e32 vcc, s88, v128
	s_cbranch_vccz .LBB0_276
	ds_bpermute_b32 v129, v210, v128
	s_waitcnt lgkmcnt(0)
	v_max_f32_e32 v129, v129, v129
	v_max_f32_e32 v128, v128, v129
	v_cmp_lt_f32_e32 vcc, s88, v128
	s_nop 0
	s_mov_b32 s98, 0
	s_nop 0
	v_cndmask_b32_e32 v128, 0, v128, vcc
	v_exp_f32_e64 v130, -v128
	v_pk_add_f32 v[64:65], v[64:65], v[128:129] op_sel_hi:[1,0] neg_lo:[0,1] neg_hi:[0,1]
	v_pk_add_f32 v[80:81], v[80:81], v[128:129] op_sel_hi:[1,0] neg_lo:[0,1] neg_hi:[0,1]
	v_pk_add_f32 v[66:67], v[66:67], v[128:129] op_sel_hi:[1,0] neg_lo:[0,1] neg_hi:[0,1]
	v_pk_mul_f32 v[46:47], v[46:47], v[130:131] op_sel_hi:[1,0]
	v_pk_mul_f32 v[44:45], v[44:45], v[130:131] op_sel_hi:[1,0]
	v_pk_mul_f32 v[42:43], v[42:43], v[130:131] op_sel_hi:[1,0]
	v_pk_mul_f32 v[40:41], v[40:41], v[130:131] op_sel_hi:[1,0]
	v_pk_mul_f32 v[38:39], v[38:39], v[130:131] op_sel_hi:[1,0]
	v_pk_mul_f32 v[36:37], v[36:37], v[130:131] op_sel_hi:[1,0]
	v_pk_mul_f32 v[34:35], v[34:35], v[130:131] op_sel_hi:[1,0]
	v_pk_mul_f32 v[32:33], v[32:33], v[130:131] op_sel_hi:[1,0]
	v_pk_mul_f32 v[62:63], v[62:63], v[130:131] op_sel_hi:[1,0]
	v_pk_mul_f32 v[60:61], v[60:61], v[130:131] op_sel_hi:[1,0]
	v_pk_mul_f32 v[58:59], v[58:59], v[130:131] op_sel_hi:[1,0]
	v_pk_mul_f32 v[56:57], v[56:57], v[130:131] op_sel_hi:[1,0]
	v_pk_mul_f32 v[54:55], v[54:55], v[130:131] op_sel_hi:[1,0]
	v_pk_mul_f32 v[52:53], v[52:53], v[130:131] op_sel_hi:[1,0]
	v_pk_mul_f32 v[50:51], v[50:51], v[130:131] op_sel_hi:[1,0]
	v_pk_mul_f32 v[48:49], v[48:49], v[130:131] op_sel_hi:[1,0]
	v_pk_mul_f32 v[30:31], v[30:31], v[130:131] op_sel_hi:[1,0]
	v_pk_mul_f32 v[28:29], v[28:29], v[130:131] op_sel_hi:[1,0]
	v_pk_mul_f32 v[26:27], v[26:27], v[130:131] op_sel_hi:[1,0]
	v_pk_mul_f32 v[24:25], v[24:25], v[130:131] op_sel_hi:[1,0]
	v_pk_mul_f32 v[22:23], v[22:23], v[130:131] op_sel_hi:[1,0]
	v_pk_mul_f32 v[20:21], v[20:21], v[130:131] op_sel_hi:[1,0]
	v_pk_mul_f32 v[18:19], v[18:19], v[130:131] op_sel_hi:[1,0]
	v_pk_mul_f32 v[16:17], v[16:17], v[130:131] op_sel_hi:[1,0]
	v_pk_mul_f32 v[14:15], v[14:15], v[130:131] op_sel_hi:[1,0]
	v_pk_mul_f32 v[12:13], v[12:13], v[130:131] op_sel_hi:[1,0]
	v_pk_mul_f32 v[10:11], v[10:11], v[130:131] op_sel_hi:[1,0]
	v_pk_mul_f32 v[8:9], v[8:9], v[130:131] op_sel_hi:[1,0]
	v_pk_mul_f32 v[6:7], v[6:7], v[130:131] op_sel_hi:[1,0]
	v_pk_mul_f32 v[4:5], v[4:5], v[130:131] op_sel_hi:[1,0]
	v_pk_mul_f32 v[2:3], v[2:3], v[130:131] op_sel_hi:[1,0]
	v_pk_mul_f32 v[0:1], v[0:1], v[130:131] op_sel_hi:[1,0]
	v_mov_b32_e32 v131, v128
	v_pk_add_f32 v[82:83], v[82:83], v[128:129] op_sel_hi:[1,0] neg_lo:[0,1] neg_hi:[0,1]
	v_pk_add_f32 v[68:69], v[68:69], v[128:129] op_sel_hi:[1,0] neg_lo:[0,1] neg_hi:[0,1]
	v_pk_add_f32 v[84:85], v[84:85], v[128:129] op_sel_hi:[1,0] neg_lo:[0,1] neg_hi:[0,1]
	v_pk_add_f32 v[70:71], v[70:71], v[128:129] op_sel_hi:[1,0] neg_lo:[0,1] neg_hi:[0,1]
	v_pk_add_f32 v[86:87], v[86:87], v[128:129] op_sel_hi:[1,0] neg_lo:[0,1] neg_hi:[0,1]
	v_pk_add_f32 v[72:73], v[72:73], v[128:129] op_sel_hi:[1,0] neg_lo:[0,1] neg_hi:[0,1]
	v_pk_add_f32 v[88:89], v[88:89], v[128:129] op_sel_hi:[1,0] neg_lo:[0,1] neg_hi:[0,1]
	v_pk_add_f32 v[74:75], v[74:75], v[128:129] op_sel_hi:[1,0] neg_lo:[0,1] neg_hi:[0,1]
	v_pk_add_f32 v[90:91], v[90:91], v[128:129] op_sel_hi:[1,0] neg_lo:[0,1] neg_hi:[0,1]
	v_pk_add_f32 v[76:77], v[76:77], v[128:129] op_sel_hi:[1,0] neg_lo:[0,1] neg_hi:[0,1]
	v_pk_add_f32 v[92:93], v[92:93], v[128:129] op_sel_hi:[1,0] neg_lo:[0,1] neg_hi:[0,1]
	v_pk_add_f32 v[78:79], v[78:79], v[128:129] op_sel_hi:[1,0] neg_lo:[0,1] neg_hi:[0,1]
	v_pk_add_f32 v[94:95], v[94:95], v[128:129] op_sel_hi:[1,0] neg_lo:[0,1] neg_hi:[0,1]
	v_pk_add_f32 v[128:129], v[206:207], v[130:131]
	v_pk_mul_f32 v[206:207], v[206:207], v[130:131]
	s_nop 0
	v_mov_b32_e32 v207, v129

.LBB0_279:
	s_and_b32 s100, s65, 0x18000
	v_add_u32_e32 v194, s100, v149
	s_cmp_lt_u32 s54, 29
	s_cselect_b32 s67, s13, s53
	s_cselect_b32 s55, 3, 0xffffffe3
	s_cselect_b32 s66, s22, s12
	s_or_b32 s70, s67, 8
	s_add_i32 s33, s55, s33
	s_ashr_i32 s71, s70, 31
	s_add_i32 s68, s33, 1
	s_lshl_b64 s[70:71], s[70:71], 18
	s_add_u32 s33, s8, s70
	s_addc_u32 s55, s9, s71
	s_ashr_i32 s69, s68, 31
	s_lshl_b64 s[70:71], s[68:69], 13
	s_add_u32 s70, s33, s70
	s_addc_u32 s71, s55, s71
	s_ashr_i32 s67, s66, 31
	s_lshl_b64 s[66:67], s[66:67], 12
	s_add_u32 s33, s10, s66
	s_addc_u32 s55, s11, s67
	s_lshl_b32 s66, s68, 6
	s_ashr_i32 s67, s66, 31
	s_lshl_b64 s[66:67], s[66:67], 1
	s_add_u32 s66, s33, s66
	s_addc_u32 s67, s55, s67
	s_add_i32 s33, s65, 0x10000
	s_and_b32 s33, s33, 0x18000
	s_add_i32 s33, s57, s33
	v_lshlrev_b32_e32 v198, 1, v150
	v_exp_f32_e32 v64, v64
	v_exp_f32_e32 v65, v65
	v_exp_f32_e32 v66, v66
	v_exp_f32_e32 v67, v67
	ds_read_b128 v[220:223], v217 offset:16384
	v_add_f32_e32 v184, v64, v65
	v_exp_f32_e32 v68, v68
	v_exp_f32_e32 v69, v69
	ds_read_b128 v[224:227], v217 offset:20480
	v_cvt_pk_bf16_f32 v64, v64, v65
	v_add_f32_e32 v185, v66, v67
	v_cvt_pk_bf16_f32 v65, v66, v67
	ds_read_b128 v[234:237], v217 offset:24576
	v_exp_f32_e32 v70, v70
	v_exp_f32_e32 v71, v71
	v_add_f32_e32 v186, v68, v69
	ds_read_b128 v[238:241], v217 offset:28672
	v_cvt_pk_bf16_f32 v66, v68, v69
	v_add_f32_e32 v184, v184, v185
	v_add_f32_e32 v187, v70, v71
	v_cvt_pk_bf16_f32 v67, v70, v71
	v_add_f32_e32 v186, v186, v187
	v_add_f32_e32 v184, v184, v186
	v_add_f32_e32 v206, v206, v184
	v_mfma_f32_32x32x16_bf16 v[32:47], v[120:123], v[64:67], v[32:47]
	v_exp_f32_e32 v72, v72
	v_exp_f32_e32 v73, v73
	v_exp_f32_e32 v74, v74
	v_exp_f32_e32 v75, v75
	v_add_f32_e32 v184, v72, v73
	v_add_u32_e32 v195, v194, v157
	v_add_u32_e32 v196, v194, v193
	s_mov_b32 m0, s33
	s_nop 0
	global_load_lds_dwordx4 v188, s[70:71]
	v_mfma_f32_32x32x16_bf16 v[48:63], v[112:115], v[64:67], v[48:63]
	v_exp_f32_e32 v76, v76
	v_exp_f32_e32 v77, v77
	v_cvt_pk_bf16_f32 v68, v72, v73
	v_add_f32_e32 v185, v74, v75
	v_cvt_pk_bf16_f32 v69, v74, v75
	v_add_u32_e32 v197, v194, v208
	v_add_u32_e32 v194, v194, v209
	v_mfma_f32_32x32x16_bf16 v[16:31], v[124:127], v[64:67], v[16:31]
	v_exp_f32_e32 v78, v78
	v_exp_f32_e32 v79, v79
	v_add_f32_e32 v186, v76, v77
	v_cvt_pk_bf16_f32 v70, v76, v77
	v_add_f32_e32 v184, v184, v185
	ds_read_b128 v[132:135], v195
	ds_read_b128 v[136:139], v196
	s_add_u32 s100, s70, 0x40000
	s_addc_u32 s101, s71, 0
	s_add_i32 m0, s33, 0x2000
	s_nop 0
	global_load_lds_dwordx4 v188, s[100:101]
	v_mfma_f32_32x32x16_bf16 v[0:15], v[116:119], v[64:67], v[0:15]
	v_add_f32_e32 v187, v78, v79
	v_cvt_pk_bf16_f32 v71, v78, v79
	v_add_f32_e32 v186, v186, v187
	v_add_f32_e32 v184, v184, v186
	v_add_f32_e32 v206, v206, v184
	ds_read_b128 v[140:143], v197
	ds_read_b128 v[128:131], v194
	ds_read_b128 v[120:123], v218 offset:16384
	ds_read_b128 v[112:115], v218 offset:20480
	ds_read_b128 v[124:127], v218 offset:24576
	ds_read_b128 v[116:119], v218 offset:28672
	s_waitcnt lgkmcnt(8)
	v_mfma_f32_32x32x16_bf16 v[32:47], v[220:223], v[68:71], v[32:47]
	v_exp_f32_e32 v80, v80
	v_exp_f32_e32 v81, v81
	v_exp_f32_e32 v82, v82
	v_exp_f32_e32 v83, v83
	v_add_f32_e32 v184, v80, v81
	s_add_i32 m0, s33, 0x4000
	s_nop 0
	global_load_lds_dwordx4 v198, s[66:67]
	v_mfma_f32_32x32x16_bf16 v[48:63], v[224:227], v[68:71], v[48:63]
	v_exp_f32_e32 v84, v84
	v_exp_f32_e32 v85, v85
	v_cvt_pk_bf16_f32 v72, v80, v81
	v_add_f32_e32 v185, v82, v83
	v_cvt_pk_bf16_f32 v73, v82, v83
	v_mfma_f32_32x32x16_bf16 v[16:31], v[234:237], v[68:71], v[16:31]
	v_exp_f32_e32 v86, v86
	v_exp_f32_e32 v87, v87
	v_add_f32_e32 v186, v84, v85
	v_cvt_pk_bf16_f32 v74, v84, v85
	v_add_f32_e32 v184, v184, v185
	s_add_u32 s100, s66, 0x40000
	s_addc_u32 s101, s67, 0
	s_add_i32 m0, s33, 0x6000
	s_nop 0
	global_load_lds_dwordx4 v198, s[100:101]
	v_mfma_f32_32x32x16_bf16 v[0:15], v[238:241], v[68:71], v[0:15]
	v_add_f32_e32 v187, v86, v87
	v_cvt_pk_bf16_f32 v75, v86, v87
	v_add_f32_e32 v186, v186, v187
	v_add_f32_e32 v184, v184, v186
	v_add_f32_e32 v206, v206, v184
	ds_read_b128 v[220:223], v219 offset:16384
	ds_read_b128 v[224:227], v219 offset:20480
	ds_read_b128 v[234:237], v219 offset:24576
	ds_read_b128 v[238:241], v219 offset:28672
	s_waitcnt lgkmcnt(4)
	v_mfma_f32_32x32x16_bf16 v[32:47], v[120:123], v[72:75], v[32:47]
	v_exp_f32_e32 v88, v88
	v_exp_f32_e32 v89, v89
	v_exp_f32_e32 v90, v90
	v_exp_f32_e32 v91, v91
	v_add_f32_e32 v184, v88, v89
	s_add_u32 s100, s70, 0x1000
	s_addc_u32 s101, s71, 0
	s_add_i32 m0, s33, 0x1000
	s_nop 0
	global_load_lds_dwordx4 v188, s[100:101]
	v_mfma_f32_32x32x16_bf16 v[48:63], v[112:115], v[72:75], v[48:63]
	v_exp_f32_e32 v92, v92
	v_exp_f32_e32 v93, v93
	v_cvt_pk_bf16_f32 v76, v88, v89
	v_add_f32_e32 v185, v90, v91
	v_cvt_pk_bf16_f32 v77, v90, v91
	v_mfma_f32_32x32x16_bf16 v[16:31], v[124:127], v[72:75], v[16:31]
	v_exp_f32_e32 v94, v94
	v_exp_f32_e32 v95, v95
	v_add_f32_e32 v186, v92, v93
	v_cvt_pk_bf16_f32 v78, v92, v93
	v_add_f32_e32 v184, v184, v185
	s_add_u32 s100, s70, 0x41000
	s_addc_u32 s101, s71, 0
	s_add_i32 m0, s33, 0x3000
	s_nop 0
	global_load_lds_dwordx4 v188, s[100:101]
	v_mfma_f32_32x32x16_bf16 v[0:15], v[116:119], v[72:75], v[0:15]
	v_add_f32_e32 v187, v94, v95
	v_cvt_pk_bf16_f32 v79, v94, v95
	v_add_f32_e32 v186, v186, v187
	v_add_f32_e32 v184, v184, v186
	v_add_f32_e32 v206, v206, v184
	ds_read_b128 v[116:119], v195 offset:4096
	ds_read_b128 v[120:123], v196 offset:4096
	ds_read_b128 v[124:127], v197 offset:4096
	ds_read_b128 v[112:115], v194 offset:4096
	s_waitcnt lgkmcnt(4)
	v_mfma_f32_32x32x16_bf16 v[32:47], v[220:223], v[76:79], v[32:47]
	s_add_u32 s100, s66, 0x20000
	s_addc_u32 s101, s67, 0
	s_add_i32 m0, s33, 0x5000
	s_nop 0
	global_load_lds_dwordx4 v198, s[100:101]
	v_mfma_f32_32x32x16_bf16 v[48:63], v[224:227], v[76:79], v[48:63]
	s_add_u32 s100, s66, 0x60000
	s_addc_u32 s101, s67, 0
	s_add_i32 m0, s33, 0x7000
	s_nop 0
	global_load_lds_dwordx4 v198, s[100:101]
	s_waitcnt lgkmcnt(0)
	s_barrier
	s_add_i32 s65, s65, 0x8000
	s_addk_i32 s23, 0x100
	s_add_i32 s36, s36, 64
	s_cmpk_eq_i32 s23, 0x1e00
	v_mfma_f32_32x32x16_bf16 v[16:31], v[234:237], v[76:79], v[16:31]
	v_mfma_f32_32x32x16_bf16 v[0:15], v[238:241], v[76:79], v[0:15]
	s_cbranch_scc1 .LBB0_284
	s_branch .Lattn_tail
.LBB0_280:
	s_and_b32 s33, s65, 0x18000
	v_add_u32_e32 v194, s33, v149
	v_exp_f32_e32 v64, v64
	v_exp_f32_e32 v65, v65
	v_exp_f32_e32 v66, v66
	v_exp_f32_e32 v67, v67
	ds_read_b128 v[220:223], v217 offset:16384
	v_add_f32_e32 v184, v64, v65
	v_exp_f32_e32 v68, v68
	v_exp_f32_e32 v69, v69
	ds_read_b128 v[224:227], v217 offset:20480
	v_cvt_pk_bf16_f32 v64, v64, v65
	v_add_f32_e32 v185, v66, v67
	v_cvt_pk_bf16_f32 v65, v66, v67
	ds_read_b128 v[234:237], v217 offset:24576
	v_exp_f32_e32 v70, v70
	v_exp_f32_e32 v71, v71
	v_add_f32_e32 v186, v68, v69
	ds_read_b128 v[238:241], v217 offset:28672
	v_cvt_pk_bf16_f32 v66, v68, v69
	v_add_f32_e32 v184, v184, v185
	v_add_f32_e32 v187, v70, v71
	v_cvt_pk_bf16_f32 v67, v70, v71
	v_add_f32_e32 v186, v186, v187
	v_add_f32_e32 v184, v184, v186
	v_add_f32_e32 v206, v206, v184
	v_mfma_f32_32x32x16_bf16 v[32:47], v[120:123], v[64:67], v[32:47]
	v_exp_f32_e32 v72, v72
	v_exp_f32_e32 v73, v73
	v_exp_f32_e32 v74, v74
	v_exp_f32_e32 v75, v75
	v_add_f32_e32 v184, v72, v73
	v_add_u32_e32 v195, v194, v157
	v_add_u32_e32 v196, v194, v193
	v_mfma_f32_32x32x16_bf16 v[48:63], v[112:115], v[64:67], v[48:63]
	v_exp_f32_e32 v76, v76
	v_exp_f32_e32 v77, v77
	v_cvt_pk_bf16_f32 v68, v72, v73
	v_add_f32_e32 v185, v74, v75
	v_cvt_pk_bf16_f32 v69, v74, v75
	v_add_u32_e32 v197, v194, v208
	v_add_u32_e32 v194, v194, v209
	v_mfma_f32_32x32x16_bf16 v[16:31], v[124:127], v[64:67], v[16:31]
	v_exp_f32_e32 v78, v78
	v_exp_f32_e32 v79, v79
	v_add_f32_e32 v186, v76, v77
	v_cvt_pk_bf16_f32 v70, v76, v77
	v_add_f32_e32 v184, v184, v185
	ds_read_b128 v[132:135], v195
	ds_read_b128 v[136:139], v196
	v_mfma_f32_32x32x16_bf16 v[0:15], v[116:119], v[64:67], v[0:15]
	v_add_f32_e32 v187, v78, v79
	v_cvt_pk_bf16_f32 v71, v78, v79
	v_add_f32_e32 v186, v186, v187
	v_add_f32_e32 v184, v184, v186
	v_add_f32_e32 v206, v206, v184
	ds_read_b128 v[140:143], v197
	ds_read_b128 v[128:131], v194
	ds_read_b128 v[120:123], v218 offset:16384
	ds_read_b128 v[112:115], v218 offset:20480
	ds_read_b128 v[124:127], v218 offset:24576
	ds_read_b128 v[116:119], v218 offset:28672
	s_waitcnt lgkmcnt(8)
	v_mfma_f32_32x32x16_bf16 v[32:47], v[220:223], v[68:71], v[32:47]
	v_exp_f32_e32 v80, v80
	v_exp_f32_e32 v81, v81
	v_exp_f32_e32 v82, v82
	v_exp_f32_e32 v83, v83
	v_add_f32_e32 v184, v80, v81
	v_mfma_f32_32x32x16_bf16 v[48:63], v[224:227], v[68:71], v[48:63]
	v_exp_f32_e32 v84, v84
	v_exp_f32_e32 v85, v85
	v_cvt_pk_bf16_f32 v72, v80, v81
	v_add_f32_e32 v185, v82, v83
	v_cvt_pk_bf16_f32 v73, v82, v83
	v_mfma_f32_32x32x16_bf16 v[16:31], v[234:237], v[68:71], v[16:31]
	v_exp_f32_e32 v86, v86
	v_exp_f32_e32 v87, v87
	v_add_f32_e32 v186, v84, v85
	v_cvt_pk_bf16_f32 v74, v84, v85
	v_add_f32_e32 v184, v184, v185
	v_mfma_f32_32x32x16_bf16 v[0:15], v[238:241], v[68:71], v[0:15]
	v_add_f32_e32 v187, v86, v87
	v_cvt_pk_bf16_f32 v75, v86, v87
	v_add_f32_e32 v186, v186, v187
	v_add_f32_e32 v184, v184, v186
	v_add_f32_e32 v206, v206, v184
	ds_read_b128 v[220:223], v219 offset:16384
	ds_read_b128 v[224:227], v219 offset:20480
	ds_read_b128 v[234:237], v219 offset:24576
	ds_read_b128 v[238:241], v219 offset:28672
	s_waitcnt lgkmcnt(4)
	v_mfma_f32_32x32x16_bf16 v[32:47], v[120:123], v[72:75], v[32:47]
	v_exp_f32_e32 v88, v88
	v_exp_f32_e32 v89, v89
	v_exp_f32_e32 v90, v90
	v_exp_f32_e32 v91, v91
	v_add_f32_e32 v184, v88, v89
	v_mfma_f32_32x32x16_bf16 v[48:63], v[112:115], v[72:75], v[48:63]
	v_exp_f32_e32 v92, v92
	v_exp_f32_e32 v93, v93
	v_cvt_pk_bf16_f32 v76, v88, v89
	v_add_f32_e32 v185, v90, v91
	v_cvt_pk_bf16_f32 v77, v90, v91
	v_mfma_f32_32x32x16_bf16 v[16:31], v[124:127], v[72:75], v[16:31]
	v_exp_f32_e32 v94, v94
	v_exp_f32_e32 v95, v95
	v_add_f32_e32 v186, v92, v93
	v_cvt_pk_bf16_f32 v78, v92, v93
	v_add_f32_e32 v184, v184, v185
	v_mfma_f32_32x32x16_bf16 v[0:15], v[116:119], v[72:75], v[0:15]
	v_add_f32_e32 v187, v94, v95
	v_cvt_pk_bf16_f32 v79, v94, v95
	v_add_f32_e32 v186, v186, v187
	v_add_f32_e32 v184, v184, v186
	v_add_f32_e32 v206, v206, v184
	ds_read_b128 v[116:119], v195 offset:4096
	ds_read_b128 v[120:123], v196 offset:4096
	ds_read_b128 v[124:127], v197 offset:4096
	ds_read_b128 v[112:115], v194 offset:4096
	s_waitcnt lgkmcnt(4)
	v_mfma_f32_32x32x16_bf16 v[32:47], v[220:223], v[76:79], v[32:47]
	v_mfma_f32_32x32x16_bf16 v[48:63], v[224:227], v[76:79], v[48:63]
	s_waitcnt lgkmcnt(0)
	s_barrier
	s_add_i32 s65, s65, 0x8000
	s_addk_i32 s23, 0x100
	s_add_i32 s36, s36, 64
	s_cmpk_eq_i32 s23, 0x1e00
	v_mfma_f32_32x32x16_bf16 v[16:31], v[234:237], v[76:79], v[16:31]
	v_mfma_f32_32x32x16_bf16 v[0:15], v[238:241], v[76:79], v[0:15]
	s_cbranch_scc1 .LBB0_284
.Lattn_tail:
	s_mov_b32 s33, s54
	s_setprio 1
	s_cmp_gt_u32 s36, 0xfffffeec
	s_mov_b64 s[54:55], -1
	s_cbranch_scc1 .LBB0_271
	s_branch .LBB0_272

	.amdhsa_kernel _Z4mega2KP
		.amdhsa_group_segment_fixed_size 0
		.amdhsa_private_segment_fixed_size 0
		.amdhsa_kernarg_size 448
		.amdhsa_user_sgpr_count 2
		.amdhsa_user_sgpr_dispatch_ptr 0
		.amdhsa_user_sgpr_queue_ptr 0
		.amdhsa_user_sgpr_kernarg_segment_ptr 1
		.amdhsa_user_sgpr_dispatch_id 0
		.amdhsa_user_sgpr_kernarg_preload_length 0
		.amdhsa_user_sgpr_kernarg_preload_offset 0
		.amdhsa_user_sgpr_private_segment_size 0
		.amdhsa_uses_dynamic_stack 0
		.amdhsa_enable_private_segment 0
		.amdhsa_system_sgpr_workgroup_id_x 1
		.amdhsa_system_sgpr_workgroup_id_y 0
		.amdhsa_system_sgpr_workgroup_id_z 0
		.amdhsa_system_sgpr_workgroup_info 0
		.amdhsa_system_vgpr_workitem_id 0
		.amdhsa_next_free_vgpr 256
		.amdhsa_next_free_sgpr 102
		.amdhsa_accum_offset 256
		.amdhsa_reserve_vcc 1
		.amdhsa_float_round_mode_32 0
		.amdhsa_float_round_mode_16_64 0
		.amdhsa_float_denorm_mode_32 3
		.amdhsa_float_denorm_mode_16_64 3
		.amdhsa_dx10_clamp 1
		.amdhsa_ieee_mode 1
		.amdhsa_fp16_overflow 0
		.amdhsa_tg_split 0
		.amdhsa_exception_fp_ieee_invalid_op 0
		.amdhsa_exception_fp_denorm_src 0
		.amdhsa_exception_fp_ieee_div_zero 0
		.amdhsa_exception_fp_ieee_overflow 0
		.amdhsa_exception_fp_ieee_underflow 0
		.amdhsa_exception_fp_ieee_inexact 0
		.amdhsa_exception_int_div_zero 0
	.end_amdhsa_kernel

amdhsa.kernels:
  - .agpr_count:     0
    .args:
      - .offset:         0
        .size:           192
        .value_kind:     by_value
      - .offset:         192
        .size:           4
        .value_kind:     hidden_block_count_x
      - .offset:         196
        .size:           4
        .value_kind:     hidden_block_count_y
      - .offset:         200
        .size:           4
        .value_kind:     hidden_block_count_z
      - .offset:         204
        .size:           2
        .value_kind:     hidden_group_size_x
      - .offset:         206
        .size:           2
        .value_kind:     hidden_group_size_y
      - .offset:         208
        .size:           2
        .value_kind:     hidden_group_size_z
      - .offset:         210
        .size:           2
        .value_kind:     hidden_remainder_x
      - .offset:         212
        .size:           2
        .value_kind:     hidden_remainder_y
      - .offset:         214
        .size:           2
        .value_kind:     hidden_remainder_z
      - .offset:         232
        .size:           8
        .value_kind:     hidden_global_offset_x
      - .offset:         240
        .size:           8
        .value_kind:     hidden_global_offset_y
      - .offset:         248
        .size:           8
        .value_kind:     hidden_global_offset_z
      - .offset:         256
        .size:           2
        .value_kind:     hidden_grid_dims
      - .offset:         312
        .size:           4
        .value_kind:     hidden_dynamic_lds_size
    .group_segment_fixed_size: 0
    .kernarg_segment_align: 8
    .kernarg_segment_size: 448
    .language:       OpenCL C
    .language_version:
      - 2
      - 0
    .max_flat_workgroup_size: 512
    .name:           _Z4mega2KP
    .private_segment_fixed_size: 0
    .sgpr_count:     108
    .sgpr_spill_count: 113
    .symbol:         _Z4mega2KP.kd
    .uniform_work_group_size: 1
    .uses_dynamic_stack: false
    .vgpr_count:     256
    .vgpr_spill_count: 0
    .wavefront_size: 64
